# compress stage-2 weight fill to LDS: 32 loads per thread in flight instead of 4 batches of 8 (on top of queue order + rope batching)
# speedup vs baseline: 1.0047x; 1.0040x over previous
.LBB0_741:
	s_or_b64 exec, exec, s[0:1]
	s_mov_b64 s[4:5], s[92:93]
	v_mov_b32_e32 v2, v230
	s_waitcnt lgkmcnt(0)
	s_barrier
	s_load_dwordx2 s[0:1], s[4:5], 0xd8
	s_movk_i32 s2, 0x4000
	v_cmp_gt_i32_e32 vcc, s2, v2
	s_and_saveexec_b64 s[14:15], vcc
	s_cbranch_execz .LBB0_754
	s_load_dwordx2 s[18:19], s[4:5], 0x70
	s_load_dwordx2 s[16:17], s[4:5], 0x88
	v_lshlrev_b32_e32 v0, 2, v2
	s_waitcnt lgkmcnt(0)
	global_load_dword v4, v0, s[18:19]
	global_load_dword v5, v0, s[18:19] offset:2048
	s_add_u32 s6, s18, 0x1000
	s_addc_u32 s7, s19, 0
	global_load_dword v6, v0, s[6:7]
	global_load_dword v7, v0, s[6:7] offset:2048
	s_add_u32 s6, s18, 0x2000
	s_addc_u32 s7, s19, 0
	global_load_dword v8, v0, s[6:7]
	global_load_dword v9, v0, s[6:7] offset:2048
	s_add_u32 s6, s18, 0x3000
	s_addc_u32 s7, s19, 0
	global_load_dword v10, v0, s[6:7]
	global_load_dword v11, v0, s[6:7] offset:2048
	s_add_u32 s6, s18, 0x4000
	s_addc_u32 s7, s19, 0
	global_load_dword v12, v0, s[6:7]
	global_load_dword v13, v0, s[6:7] offset:2048
	s_add_u32 s6, s18, 0x5000
	s_addc_u32 s7, s19, 0
	global_load_dword v14, v0, s[6:7]
	global_load_dword v15, v0, s[6:7] offset:2048
	s_add_u32 s6, s18, 0x6000
	s_addc_u32 s7, s19, 0
	global_load_dword v16, v0, s[6:7]
	global_load_dword v17, v0, s[6:7] offset:2048
	s_add_u32 s6, s18, 0x7000
	s_addc_u32 s7, s19, 0
	global_load_dword v18, v0, s[6:7]
	global_load_dword v19, v0, s[6:7] offset:2048
	global_load_dword v20, v0, s[16:17]
	global_load_dword v21, v0, s[16:17] offset:2048
	s_add_u32 s6, s16, 0x1000
	s_addc_u32 s7, s17, 0
	global_load_dword v22, v0, s[6:7]
	global_load_dword v23, v0, s[6:7] offset:2048
	s_add_u32 s6, s16, 0x2000
	s_addc_u32 s7, s17, 0
	global_load_dword v24, v0, s[6:7]
	global_load_dword v25, v0, s[6:7] offset:2048
	s_add_u32 s6, s16, 0x3000
	s_addc_u32 s7, s17, 0
	global_load_dword v26, v0, s[6:7]
	global_load_dword v27, v0, s[6:7] offset:2048
	s_add_u32 s6, s16, 0x4000
	s_addc_u32 s7, s17, 0
	global_load_dword v28, v0, s[6:7]
	global_load_dword v29, v0, s[6:7] offset:2048
	s_add_u32 s6, s16, 0x5000
	s_addc_u32 s7, s17, 0
	global_load_dword v30, v0, s[6:7]
	global_load_dword v31, v0, s[6:7] offset:2048
	s_add_u32 s6, s16, 0x6000
	s_addc_u32 s7, s17, 0
	global_load_dword v32, v0, s[6:7]
	global_load_dword v33, v0, s[6:7] offset:2048
	s_add_u32 s6, s16, 0x7000
	s_addc_u32 s7, s17, 0
	global_load_dword v34, v0, s[6:7]
	global_load_dword v35, v0, s[6:7] offset:2048
	s_waitcnt vmcnt(28)
	ds_write_b32 v0, v4
	ds_write_b32 v0, v5 offset:2048
	ds_write_b32 v0, v6 offset:4096
	ds_write_b32 v0, v7 offset:6144
	s_waitcnt vmcnt(24)
	ds_write_b32 v0, v8 offset:8192
	ds_write_b32 v0, v9 offset:10240
	ds_write_b32 v0, v10 offset:12288
	ds_write_b32 v0, v11 offset:14336
	s_waitcnt vmcnt(20)
	ds_write_b32 v0, v12 offset:16384
	ds_write_b32 v0, v13 offset:18432
	ds_write_b32 v0, v14 offset:20480
	ds_write_b32 v0, v15 offset:22528
	s_waitcnt vmcnt(16)
	ds_write_b32 v0, v16 offset:24576
	ds_write_b32 v0, v17 offset:26624
	ds_write_b32 v0, v18 offset:28672
	ds_write_b32 v0, v19 offset:30720
	s_waitcnt vmcnt(12)
	ds_write_b32 v0, v20 offset:32768
	ds_write_b32 v0, v21 offset:34816
	ds_write_b32 v0, v22 offset:36864
	ds_write_b32 v0, v23 offset:38912
	s_waitcnt vmcnt(8)
	ds_write_b32 v0, v24 offset:40960
	ds_write_b32 v0, v25 offset:43008
	ds_write_b32 v0, v26 offset:45056
	ds_write_b32 v0, v27 offset:47104
	s_waitcnt vmcnt(4)
	ds_write_b32 v0, v28 offset:49152
	ds_write_b32 v0, v29 offset:51200
	ds_write_b32 v0, v30 offset:53248
	ds_write_b32 v0, v31 offset:55296
	s_waitcnt vmcnt(0)
	ds_write_b32 v0, v32 offset:57344
	ds_write_b32 v0, v33 offset:59392
	ds_write_b32 v0, v34 offset:61440
	ds_write_b32 v0, v35 offset:63488
